# hand-written Swiglu epilogue fast path (rstd LDS reads batched, 32-bit offsets); plus LRU prefetch, sc1 stores, batched epilogue loads
# speedup vs baseline: 1.0231x; 1.0096x over previous
; #define PG8_STAGE(bufoff, gbase, voff) do { _Pragma("unroll") for (int _i = 0; _i < 2; ++_i) \
;         __builtin_amdgcn_global_load_lds((const unsigned*)((const char*)(gbase) + (voff)[_i]), (PG8_LAS unsigned*)(lds + (bufoff) + ldsw + _i * 8192), 16, 0, 0); } while (0)
; #define PG8_LDA(dst, b, h) do { _Pragma("unroll") for (int m = 0; m < 4; ++m) _Pragma("unroll") for (int k = 0; k < 2; ++k) dst[m][k] = *(const PG8_LAS bf16x8*)(lds + PG8_SA(b, h) + aoff + m * 2048 + k * 1024); } while (0)
; #define PG8_LDB(dst, b, h) do { _Pragma("unroll") for (int n = 0; n < 2; ++n) _Pragma("unroll") for (int k = 0; k < 2; ++k) dst[n][k] = *(const PG8_LAS bf16x8*)(lds + PG8_SB(b, h) + boff + n * 2048 + k * 1024); } while (0)
; #define PG8_MMA(ai, bj, At, Bt) do { __builtin_amdgcn_s_setprio(1); _Pragma("unroll") for (int m = 0; m < 4; ++m) _Pragma("unroll") for (int n = 0; n < 2; ++n) _Pragma("unroll") for (int k = 0; k < 2; ++k) \
;         acc[ai][bj][m][n] = __builtin_amdgcn_mfma_f32_16x16x32_bf16(Bt[n][k], At[m][k], acc[ai][bj][m][n], 0, 0, 0); __builtin_amdgcn_s_setprio(0); } while (0)
; #define PG8_WAIT_V(n) asm volatile("s_waitcnt vmcnt(" #n ")" ::: "memory")
; #define PG8_WAIT_L(n) asm volatile("s_waitcnt lgkmcnt(" #n ")" ::: "memory")
; #define PG8_BAR __builtin_amdgcn_s_barrier()
; template <class Epi, class Sched, bool ALIGN_EPI = false, bool SP2 = false>
; __device__ __forceinline__ void gemm_phase(PG8_LAS unsigned char* lds, const Gemm g, const Sched& S, const Epi& E) {
;     ...
;             const char* a1 = cA + (size_t)(t + 1) * kstep;
;             const char* a2 = last ? nA : cA + (size_t)(t + 2) * kstep; const char* b2 = last ? nB : cB + (size_t)(t + 2) * kstep;
;             const char* a3 = a2 + kstep; const char* b3 = b2 + kstep;
;             if (last && has_next) S.a_ready(nxt);
;             if constexpr (SP2) {
;             PG8_LDB(B0, 0, 0); PG8_LDB(B1, 0, 1); PG8_SCHED; PG8_LDA(At, 0, 0); PG8_STAGE(PG8_SA(1, 1), a1 + hstep, voffA);
;             PG8_WAIT_V(8); PG8_WAIT_L(0); PG8_BAR; PG8_MMA(0, 0, At, B0); PG8_MMA(0, 1, At, B1); PG8_BAR; PG8_SCHED;
;             PG8_LDA(At, 0, 1); PG8_STAGE(PG8_SB(0, 0), b2, voffB); PG8_STAGE(PG8_SB(0, 1), b2 + hstep, voffB); PG8_STAGE(PG8_SA(0, 0), a2, voffA);
;             PG8_WAIT_V(8); PG8_WAIT_L(0); PG8_BAR; PG8_MMA(1, 0, At, B0); PG8_MMA(1, 1, At, B1); PG8_BAR; PG8_SCHED;
.LBB0_225:
	s_add_u32 s24, s22, 0xfffc0080
	s_addc_u32 s25, s23, -1
	s_add_i32 s52, 0, 0x10000
	s_cmp_eq_u32 s51, 12
	s_cselect_b32 s27, s5, s25
	s_cselect_b32 s26, s15, s24
	v_add_u32_e32 v138, s52, v149
	s_cselect_b32 s25, s13, s50
	s_cselect_b32 s24, s21, s49
	s_add_i32 s55, 0, 0x14000
	ds_read_b128 v[144:147], v138
	ds_read_b128 v[154:157], v138 offset:1024
	ds_read_b128 v[158:161], v138 offset:2048
	ds_read_b128 v[162:165], v138 offset:3072
	v_add_u32_e32 v138, s55, v149
	ds_read_b128 v[166:169], v138
	ds_read_b128 v[170:173], v138 offset:1024
	ds_read_b128 v[174:177], v138 offset:2048
	ds_read_b128 v[178:181], v138 offset:3072
	v_lshl_add_u64 v[138:139], s[22:23], 0, v[136:137]
	s_add_i32 m0, s41, 0xc000
	ds_read_b128 v[182:185], v152
	ds_read_b128 v[186:189], v152 offset:1024
	ds_read_b128 v[190:193], v152 offset:2048
	ds_read_b128 v[194:197], v152 offset:3072
	ds_read_b128 v[198:201], v152 offset:4096
	ds_read_b128 v[202:205], v152 offset:5120
	ds_read_b128 v[224:227], v152 offset:6144
	ds_read_b128 v[228:231], v152 offset:7168
	global_load_lds_dwordx4 v[138:139], off
	v_lshl_add_u64 v[138:139], s[22:23], 0, v[142:143]
	s_add_i32 m0, s41, 0xe000
	s_nop 0
	global_load_lds_dwordx4 v[138:139], off
	s_waitcnt vmcnt(8)
	s_waitcnt lgkmcnt(0)
	s_barrier
	s_setprio 1
	s_waitcnt lgkmcnt(0)
	v_mfma_f32_16x16x32_bf16 v[126:129], v[144:147], v[182:185], v[126:129]
	v_mfma_f32_16x16x32_bf16 v[122:125], v[158:161], v[182:185], v[122:125]
	v_mfma_f32_16x16x32_bf16 v[110:113], v[144:147], v[190:193], v[110:113]
	v_mfma_f32_16x16x32_bf16 v[106:109], v[158:161], v[190:193], v[106:109]
	v_mfma_f32_16x16x32_bf16 v[94:97], v[144:147], v[198:201], v[94:97]
	v_mfma_f32_16x16x32_bf16 v[90:93], v[158:161], v[198:201], v[90:93]
	v_mfma_f32_16x16x32_bf16 v[78:81], v[144:147], v[224:227], v[78:81]
	v_mfma_f32_16x16x32_bf16 v[74:77], v[158:161], v[224:227], v[74:77]
	v_mfma_f32_16x16x32_bf16 v[126:129], v[154:157], v[186:189], v[126:129]
	v_mfma_f32_16x16x32_bf16 v[122:125], v[162:165], v[186:189], v[122:125]
	v_mfma_f32_16x16x32_bf16 v[110:113], v[154:157], v[194:197], v[110:113]
	v_mfma_f32_16x16x32_bf16 v[106:109], v[162:165], v[194:197], v[106:109]
	v_mfma_f32_16x16x32_bf16 v[94:97], v[154:157], v[202:205], v[94:97]
	v_mfma_f32_16x16x32_bf16 v[90:93], v[162:165], v[202:205], v[90:93]
	v_mfma_f32_16x16x32_bf16 v[78:81], v[154:157], v[228:231], v[78:81]
	v_mfma_f32_16x16x32_bf16 v[74:77], v[162:165], v[228:231], v[74:77]
	s_setprio 0
	s_setprio 1
	v_mfma_f32_16x16x32_bf16 v[118:121], v[166:169], v[182:185], v[118:121]
	v_mfma_f32_16x16x32_bf16 v[114:117], v[174:177], v[182:185], v[114:117]
	v_mfma_f32_16x16x32_bf16 v[102:105], v[166:169], v[190:193], v[102:105]
	v_mfma_f32_16x16x32_bf16 v[98:101], v[174:177], v[190:193], v[98:101]
	v_mfma_f32_16x16x32_bf16 v[86:89], v[166:169], v[198:201], v[86:89]
	v_mfma_f32_16x16x32_bf16 v[82:85], v[174:177], v[198:201], v[82:85]
	v_mfma_f32_16x16x32_bf16 v[70:73], v[166:169], v[224:227], v[70:73]
	v_mfma_f32_16x16x32_bf16 v[66:69], v[174:177], v[224:227], v[66:69]
	v_mfma_f32_16x16x32_bf16 v[118:121], v[170:173], v[186:189], v[118:121]
	v_mfma_f32_16x16x32_bf16 v[114:117], v[178:181], v[186:189], v[114:117]
	v_mfma_f32_16x16x32_bf16 v[102:105], v[170:173], v[194:197], v[102:105]
	v_mfma_f32_16x16x32_bf16 v[98:101], v[178:181], v[194:197], v[98:101]
	v_mfma_f32_16x16x32_bf16 v[86:89], v[170:173], v[202:205], v[86:89]
	v_mfma_f32_16x16x32_bf16 v[82:85], v[178:181], v[202:205], v[82:85]
	v_mfma_f32_16x16x32_bf16 v[70:73], v[170:173], v[228:231], v[70:73]
	v_mfma_f32_16x16x32_bf16 v[66:69], v[178:181], v[228:231], v[66:69]
	s_setprio 0
	s_barrier
	s_add_i32 s52, s52, s31
	v_lshl_add_u64 v[138:139], s[24:25], 0, v[0:1]
	s_mov_b32 m0, s52
	ds_read_b128 v[182:185], v152 offset:16384
	ds_read_b128 v[186:189], v152 offset:17408
	ds_read_b128 v[190:193], v152 offset:18432
	ds_read_b128 v[194:197], v152 offset:19456
	ds_read_b128 v[198:201], v152 offset:20480
	ds_read_b128 v[202:205], v152 offset:21504
	ds_read_b128 v[224:227], v152 offset:22528
	ds_read_b128 v[228:231], v152 offset:23552
	global_load_lds_dwordx4 v[138:139], off
	s_add_i32 m0, s52, 0x2000
	s_add_u32 s52, s24, 0x40000
	v_lshl_add_u64 v[140:141], s[24:25], 0, v[134:135]
	s_addc_u32 s53, s25, 0
	s_add_i32 s55, s55, s31
	global_load_lds_dwordx4 v[140:141], off
	v_lshl_add_u64 v[232:233], s[52:53], 0, v[0:1]
	s_mov_b32 m0, s55
	v_lshl_add_u64 v[234:235], s[26:27], 0, v[132:133]
	global_load_lds_dwordx4 v[232:233], off
	v_lshl_add_u64 v[232:233], s[52:53], 0, v[134:135]
	s_add_i32 m0, s55, 0x2000
	s_nop 0
	global_load_lds_dwordx4 v[232:233], off
	v_lshl_add_u64 v[232:233], s[26:27], 0, v[130:131]
	s_mov_b32 m0, s41
	s_nop 0
	global_load_lds_dwordx4 v[232:233], off
	s_mov_b32 m0, s42
	s_nop 0
	global_load_lds_dwordx4 v[234:235], off
	s_waitcnt vmcnt(8)
	s_waitcnt lgkmcnt(0)
	s_barrier
; #define PG8_STAGE(bufoff, gbase, voff) do { _Pragma("unroll") for (int _i = 0; _i < 2; ++_i) \
;         __builtin_amdgcn_global_load_lds((const unsigned*)((const char*)(gbase) + (voff)[_i]), (PG8_LAS unsigned*)(lds + (bufoff) + ldsw + _i * 8192), 16, 0, 0); } while (0)
; #define PG8_LDA(dst, b, h) do { _Pragma("unroll") for (int m = 0; m < 4; ++m) _Pragma("unroll") for (int k = 0; k < 2; ++k) dst[m][k] = *(const PG8_LAS bf16x8*)(lds + PG8_SA(b, h) + aoff + m * 2048 + k * 1024); } while (0)
; #define PG8_LDB(dst, b, h) do { _Pragma("unroll") for (int n = 0; n < 2; ++n) _Pragma("unroll") for (int k = 0; k < 2; ++k) dst[n][k] = *(const PG8_LAS bf16x8*)(lds + PG8_SB(b, h) + boff + n * 2048 + k * 1024); } while (0)
; #define PG8_MMA(ai, bj, At, Bt) do { __builtin_amdgcn_s_setprio(1); _Pragma("unroll") for (int m = 0; m < 4; ++m) _Pragma("unroll") for (int n = 0; n < 2; ++n) _Pragma("unroll") for (int k = 0; k < 2; ++k) \
;         acc[ai][bj][m][n] = __builtin_amdgcn_mfma_f32_16x16x32_bf16(Bt[n][k], At[m][k], acc[ai][bj][m][n], 0, 0, 0); __builtin_amdgcn_s_setprio(0); } while (0)
; #define PG8_WAIT_V(n) asm volatile("s_waitcnt vmcnt(" #n ")" ::: "memory")
; #define PG8_WAIT_L(n) asm volatile("s_waitcnt lgkmcnt(" #n ")" ::: "memory")
; #define PG8_BAR __builtin_amdgcn_s_barrier()
; #define PG8_SCHED __builtin_amdgcn_sched_barrier(0)
; template <class Epi, class Sched, bool ALIGN_EPI = false, bool SP2 = false>
; __device__ __forceinline__ void gemm_phase(PG8_LAS unsigned char* lds, const Gemm g, const Sched& S, const Epi& E) {
;     ...
;             PG8_WAIT_V(8); PG8_WAIT_L(0); PG8_BAR; PG8_MMA(1, 0, At, B0); PG8_MMA(1, 1, At, B1); PG8_BAR; PG8_SCHED;
;             PG8_LDB(B0, 1, 0); PG8_LDB(B1, 1, 1); PG8_SCHED; PG8_LDA(At, 1, 0); PG8_STAGE(PG8_SA(0, 1), a2 + hstep, voffA);
;             PG8_WAIT_V(8); PG8_WAIT_L(0); PG8_BAR; PG8_MMA(0, 0, At, B0); PG8_MMA(0, 1, At, B1); PG8_BAR; PG8_SCHED;
	s_setprio 1
	s_waitcnt lgkmcnt(0)
	v_mfma_f32_16x16x32_bf16 v[62:65], v[144:147], v[182:185], v[62:65]
	v_mfma_f32_16x16x32_bf16 v[58:61], v[158:161], v[182:185], v[58:61]
	v_mfma_f32_16x16x32_bf16 v[46:49], v[144:147], v[190:193], v[46:49]
	v_mfma_f32_16x16x32_bf16 v[42:45], v[158:161], v[190:193], v[42:45]
	v_mfma_f32_16x16x32_bf16 v[30:33], v[144:147], v[198:201], v[30:33]
	v_mfma_f32_16x16x32_bf16 v[26:29], v[158:161], v[198:201], v[26:29]
	v_mfma_f32_16x16x32_bf16 v[14:17], v[144:147], v[224:227], v[14:17]
	v_mfma_f32_16x16x32_bf16 v[10:13], v[158:161], v[224:227], v[10:13]
	v_mfma_f32_16x16x32_bf16 v[62:65], v[154:157], v[186:189], v[62:65]
	v_mfma_f32_16x16x32_bf16 v[58:61], v[162:165], v[186:189], v[58:61]
	v_mfma_f32_16x16x32_bf16 v[46:49], v[154:157], v[194:197], v[46:49]
	v_mfma_f32_16x16x32_bf16 v[42:45], v[162:165], v[194:197], v[42:45]
	v_mfma_f32_16x16x32_bf16 v[30:33], v[154:157], v[202:205], v[30:33]
	v_mfma_f32_16x16x32_bf16 v[26:29], v[162:165], v[202:205], v[26:29]
	v_mfma_f32_16x16x32_bf16 v[14:17], v[154:157], v[228:231], v[14:17]
	v_mfma_f32_16x16x32_bf16 v[10:13], v[162:165], v[228:231], v[10:13]
	s_setprio 0
	s_setprio 1
	v_mfma_f32_16x16x32_bf16 v[54:57], v[166:169], v[182:185], v[54:57]
	v_mfma_f32_16x16x32_bf16 v[50:53], v[174:177], v[182:185], v[50:53]
	v_mfma_f32_16x16x32_bf16 v[38:41], v[166:169], v[190:193], v[38:41]
	v_mfma_f32_16x16x32_bf16 v[34:37], v[174:177], v[190:193], v[34:37]
	v_mfma_f32_16x16x32_bf16 v[22:25], v[166:169], v[198:201], v[22:25]
	v_mfma_f32_16x16x32_bf16 v[18:21], v[174:177], v[198:201], v[18:21]
	v_mfma_f32_16x16x32_bf16 v[6:9], v[166:169], v[224:227], v[6:9]
	v_mfma_f32_16x16x32_bf16 v[2:5], v[174:177], v[224:227], v[2:5]
	v_mfma_f32_16x16x32_bf16 v[54:57], v[170:173], v[186:189], v[54:57]
	v_mfma_f32_16x16x32_bf16 v[50:53], v[178:181], v[186:189], v[50:53]
	v_mfma_f32_16x16x32_bf16 v[38:41], v[170:173], v[194:197], v[38:41]
	v_mfma_f32_16x16x32_bf16 v[34:37], v[178:181], v[194:197], v[34:37]
	v_mfma_f32_16x16x32_bf16 v[22:25], v[170:173], v[202:205], v[22:25]
	v_mfma_f32_16x16x32_bf16 v[18:21], v[178:181], v[202:205], v[18:21]
	v_mfma_f32_16x16x32_bf16 v[6:9], v[170:173], v[228:231], v[6:9]
	v_mfma_f32_16x16x32_bf16 v[2:5], v[178:181], v[228:231], v[2:5]
	s_setprio 0
	s_barrier
	s_add_i32 s52, 0, 0x18000
	v_add_u32_e32 v153, s52, v149
	s_add_i32 s53, 0, 0x1c000
	ds_read_b128 v[144:147], v153
	ds_read_b128 v[154:157], v153 offset:1024
	ds_read_b128 v[158:161], v153 offset:2048
	ds_read_b128 v[162:165], v153 offset:3072
	v_add_u32_e32 v153, s53, v149
	ds_read_b128 v[166:169], v153
	ds_read_b128 v[170:173], v153 offset:1024
	ds_read_b128 v[174:177], v153 offset:2048
	ds_read_b128 v[178:181], v153 offset:3072
	s_add_u32 s26, s26, 0x40000
	s_addc_u32 s27, s27, 0
	s_mov_b32 m0, s43
	v_lshl_add_u64 v[236:237], s[26:27], 0, v[130:131]
	ds_read_b128 v[182:185], v152 offset:32768
	ds_read_b128 v[186:189], v152 offset:33792
	ds_read_b128 v[190:193], v152 offset:34816
	ds_read_b128 v[194:197], v152 offset:35840
	ds_read_b128 v[198:201], v152 offset:36864
	ds_read_b128 v[202:205], v152 offset:37888
	ds_read_b128 v[224:227], v152 offset:38912
	ds_read_b128 v[228:231], v152 offset:39936
	global_load_lds_dwordx4 v[236:237], off
	v_lshl_add_u64 v[236:237], s[26:27], 0, v[132:133]
	s_mov_b32 m0, s44
	s_nop 0
	global_load_lds_dwordx4 v[236:237], off
	s_waitcnt vmcnt(8)
	s_waitcnt lgkmcnt(0)
	s_barrier
	s_setprio 1
	s_waitcnt lgkmcnt(0)
	v_mfma_f32_16x16x32_bf16 v[126:129], v[144:147], v[182:185], v[126:129]
	v_mfma_f32_16x16x32_bf16 v[122:125], v[158:161], v[182:185], v[122:125]
	v_mfma_f32_16x16x32_bf16 v[110:113], v[144:147], v[190:193], v[110:113]
	v_mfma_f32_16x16x32_bf16 v[106:109], v[158:161], v[190:193], v[106:109]
	v_mfma_f32_16x16x32_bf16 v[94:97], v[144:147], v[198:201], v[94:97]
	v_mfma_f32_16x16x32_bf16 v[90:93], v[158:161], v[198:201], v[90:93]
	v_mfma_f32_16x16x32_bf16 v[78:81], v[144:147], v[224:227], v[78:81]
	v_mfma_f32_16x16x32_bf16 v[74:77], v[158:161], v[224:227], v[74:77]
	v_mfma_f32_16x16x32_bf16 v[126:129], v[154:157], v[186:189], v[126:129]
	v_mfma_f32_16x16x32_bf16 v[122:125], v[162:165], v[186:189], v[122:125]
	v_mfma_f32_16x16x32_bf16 v[110:113], v[154:157], v[194:197], v[110:113]
	v_mfma_f32_16x16x32_bf16 v[106:109], v[162:165], v[194:197], v[106:109]
	v_mfma_f32_16x16x32_bf16 v[94:97], v[154:157], v[202:205], v[94:97]
	v_mfma_f32_16x16x32_bf16 v[90:93], v[162:165], v[202:205], v[90:93]
	v_mfma_f32_16x16x32_bf16 v[78:81], v[154:157], v[228:231], v[78:81]
	v_mfma_f32_16x16x32_bf16 v[74:77], v[162:165], v[228:231], v[74:77]
	s_setprio 0
	s_setprio 1
	v_mfma_f32_16x16x32_bf16 v[118:121], v[166:169], v[182:185], v[118:121]
	v_mfma_f32_16x16x32_bf16 v[114:117], v[174:177], v[182:185], v[114:117]
	v_mfma_f32_16x16x32_bf16 v[102:105], v[166:169], v[190:193], v[102:105]
	v_mfma_f32_16x16x32_bf16 v[98:101], v[174:177], v[190:193], v[98:101]
	v_mfma_f32_16x16x32_bf16 v[86:89], v[166:169], v[198:201], v[86:89]
	v_mfma_f32_16x16x32_bf16 v[82:85], v[174:177], v[198:201], v[82:85]
	v_mfma_f32_16x16x32_bf16 v[70:73], v[166:169], v[224:227], v[70:73]
	v_mfma_f32_16x16x32_bf16 v[66:69], v[174:177], v[224:227], v[66:69]
	v_mfma_f32_16x16x32_bf16 v[118:121], v[170:173], v[186:189], v[118:121]
	v_mfma_f32_16x16x32_bf16 v[114:117], v[178:181], v[186:189], v[114:117]
	v_mfma_f32_16x16x32_bf16 v[102:105], v[170:173], v[194:197], v[102:105]
	v_mfma_f32_16x16x32_bf16 v[98:101], v[178:181], v[194:197], v[98:101]
	v_mfma_f32_16x16x32_bf16 v[86:89], v[170:173], v[202:205], v[86:89]
	v_mfma_f32_16x16x32_bf16 v[82:85], v[178:181], v[202:205], v[82:85]
	v_mfma_f32_16x16x32_bf16 v[70:73], v[170:173], v[228:231], v[70:73]
	v_mfma_f32_16x16x32_bf16 v[66:69], v[178:181], v[228:231], v[66:69]
	s_setprio 0
	s_barrier
; #define PG8_STAGE(bufoff, gbase, voff) do { _Pragma("unroll") for (int _i = 0; _i < 2; ++_i) \
;         __builtin_amdgcn_global_load_lds((const unsigned*)((const char*)(gbase) + (voff)[_i]), (PG8_LAS unsigned*)(lds + (bufoff) + ldsw + _i * 8192), 16, 0, 0); } while (0)
; #define PG8_LDA(dst, b, h) do { _Pragma("unroll") for (int m = 0; m < 4; ++m) _Pragma("unroll") for (int k = 0; k < 2; ++k) dst[m][k] = *(const PG8_LAS bf16x8*)(lds + PG8_SA(b, h) + aoff + m * 2048 + k * 1024); } while (0)
; #define PG8_WAIT_V(n) asm volatile("s_waitcnt vmcnt(" #n ")" ::: "memory")
; #define PG8_WAIT_L(n) asm volatile("s_waitcnt lgkmcnt(" #n ")" ::: "memory")
; #define PG8_BAR __builtin_amdgcn_s_barrier()
; #define PG8_SCHED __builtin_amdgcn_sched_barrier(0)
; template <class Epi, class Sched, bool ALIGN_EPI = false, bool SP2 = false>
; __device__ __forceinline__ void gemm_phase(PG8_LAS unsigned char* lds, const Gemm g, const Sched& S, const Epi& E) {
;     ...
;             PG8_LDA(At, 1, 1); PG8_STAGE(PG8_SB(1, 0), b3, voffB); PG8_STAGE(PG8_SB(1, 1), b3 + hstep, voffB); PG8_STAGE(PG8_SA(1, 0), a3, voffA);
;             PG8_WAIT_V(8); PG8_WAIT_L(0); PG8_BAR; PG8_MMA(1, 0, At, B0); PG8_MMA(1, 1, At, B1); PG8_BAR; PG8_SCHED;
;     __device__ __forceinline__ void operator()(const f32x4 (&acc)[2][2][4][2], const Unit& u, int wr, int wc, int fr, int fq) const {
;     ...
;             for (int m = 0; m < 4; ++m) {
;                 const int row = row0 + ai * 128 + m * 16; const float rs = (u.pm == pm0) ? RS[row & 255] : row_rstd(ss, row), rsl = -LOG2E_ * rs, rs2 = rs * rs;
;                 f32x4 t[2], q[2], e[2];
; #pragma unroll
;                 for (int n = 0; n < 2; ++n) { t[n] = acc[ai][0][m][n] * rsl; q[n] = acc[ai][0][m][n] * acc[ai][1][m][n]; }
; #pragma unroll
;                 for (int n = 0; n < 2; ++n)
; #pragma unroll
;                     for (int j = 0; j < 4; ++j) e[n][j] = __builtin_amdgcn_exp2f(t[n][j]);
; #pragma unroll
;                 for (int n = 0; n < 2; ++n) { e[n] = e[n] + 1.0f; q[n] = q[n] * rs2; }
; #pragma unroll
;                 for (int n = 0; n < 2; ++n)
; #pragma unroll
;                     for (int j = 0; j < 4; ++j) e[n][j] = __builtin_amdgcn_rcpf(e[n][j]);
;                 __builtin_nontemporal_store(pack8(q[0] * e[0], q[1] * e[1]), (u32x4*)(O + (size_t)row * DFF + col0));
	s_add_i32 s26, s52, s31
	v_lshl_add_u64 v[138:139], v[138:139], 0, s[86:87]
	s_mov_b32 m0, s26
	ds_read_b128 v[182:185], v152 offset:49152
	ds_read_b128 v[186:189], v152 offset:50176
	ds_read_b128 v[190:193], v152 offset:51200
	ds_read_b128 v[194:197], v152 offset:52224
	ds_read_b128 v[198:201], v152 offset:53248
	ds_read_b128 v[202:205], v152 offset:54272
	ds_read_b128 v[224:227], v152 offset:55296
	ds_read_b128 v[228:231], v152 offset:56320
	global_load_lds_dwordx4 v[138:139], off
	s_add_i32 m0, s26, 0x2000
	s_add_u32 s24, s24, 0x40080
	v_lshl_add_u64 v[138:139], v[140:141], 0, s[86:87]
	s_addc_u32 s25, s25, 0
	s_add_i32 s26, s53, s31
	global_load_lds_dwordx4 v[138:139], off
	v_lshl_add_u64 v[138:139], s[24:25], 0, v[0:1]
	s_mov_b32 m0, s26
	s_nop 0
	global_load_lds_dwordx4 v[138:139], off
	v_lshl_add_u64 v[138:139], s[24:25], 0, v[134:135]
	s_add_i32 m0, s26, 0x2000
	s_nop 0
	global_load_lds_dwordx4 v[138:139], off
	v_lshl_add_u64 v[138:139], v[232:233], 0, s[86:87]
	s_mov_b32 m0, s45
	s_nop 0
	global_load_lds_dwordx4 v[138:139], off
	v_lshl_add_u64 v[138:139], v[234:235], 0, s[86:87]
	s_mov_b32 m0, s46
	s_nop 0
	global_load_lds_dwordx4 v[138:139], off
	s_waitcnt vmcnt(8)
	s_waitcnt lgkmcnt(0)
	s_barrier
	s_setprio 1
	s_waitcnt lgkmcnt(0)
	v_mfma_f32_16x16x32_bf16 v[62:65], v[144:147], v[182:185], v[62:65]
	v_mfma_f32_16x16x32_bf16 v[58:61], v[158:161], v[182:185], v[58:61]
	v_mfma_f32_16x16x32_bf16 v[46:49], v[144:147], v[190:193], v[46:49]
	v_mfma_f32_16x16x32_bf16 v[42:45], v[158:161], v[190:193], v[42:45]
	v_mfma_f32_16x16x32_bf16 v[30:33], v[144:147], v[198:201], v[30:33]
	v_mfma_f32_16x16x32_bf16 v[26:29], v[158:161], v[198:201], v[26:29]
	v_mfma_f32_16x16x32_bf16 v[14:17], v[144:147], v[224:227], v[14:17]
	v_mfma_f32_16x16x32_bf16 v[10:13], v[158:161], v[224:227], v[10:13]
	v_mfma_f32_16x16x32_bf16 v[62:65], v[154:157], v[186:189], v[62:65]
	v_mfma_f32_16x16x32_bf16 v[58:61], v[162:165], v[186:189], v[58:61]
	v_mfma_f32_16x16x32_bf16 v[46:49], v[154:157], v[194:197], v[46:49]
	v_mfma_f32_16x16x32_bf16 v[42:45], v[162:165], v[194:197], v[42:45]
	v_mfma_f32_16x16x32_bf16 v[30:33], v[154:157], v[202:205], v[30:33]
	v_mfma_f32_16x16x32_bf16 v[26:29], v[162:165], v[202:205], v[26:29]
	v_mfma_f32_16x16x32_bf16 v[14:17], v[154:157], v[228:231], v[14:17]
	v_mfma_f32_16x16x32_bf16 v[10:13], v[162:165], v[228:231], v[10:13]
	s_setprio 0
	s_setprio 1
	v_mfma_f32_16x16x32_bf16 v[54:57], v[166:169], v[182:185], v[54:57]
	v_mfma_f32_16x16x32_bf16 v[50:53], v[174:177], v[182:185], v[50:53]
	v_mfma_f32_16x16x32_bf16 v[38:41], v[166:169], v[190:193], v[38:41]
	v_mfma_f32_16x16x32_bf16 v[34:37], v[174:177], v[190:193], v[34:37]
	v_mfma_f32_16x16x32_bf16 v[22:25], v[166:169], v[198:201], v[22:25]
	v_mfma_f32_16x16x32_bf16 v[18:21], v[174:177], v[198:201], v[18:21]
	v_mfma_f32_16x16x32_bf16 v[6:9], v[166:169], v[224:227], v[6:9]
	v_mfma_f32_16x16x32_bf16 v[2:5], v[174:177], v[224:227], v[2:5]
	v_mfma_f32_16x16x32_bf16 v[54:57], v[170:173], v[186:189], v[54:57]
	v_mfma_f32_16x16x32_bf16 v[50:53], v[178:181], v[186:189], v[50:53]
	v_mfma_f32_16x16x32_bf16 v[38:41], v[170:173], v[194:197], v[38:41]
	v_mfma_f32_16x16x32_bf16 v[34:37], v[178:181], v[194:197], v[34:37]
	v_mfma_f32_16x16x32_bf16 v[22:25], v[170:173], v[202:205], v[22:25]
	v_mfma_f32_16x16x32_bf16 v[18:21], v[178:181], v[202:205], v[18:21]
	v_mfma_f32_16x16x32_bf16 v[6:9], v[170:173], v[228:231], v[6:9]
	v_mfma_f32_16x16x32_bf16 v[2:5], v[178:181], v[228:231], v[2:5]
	s_setprio 0
	s_barrier
	s_add_i32 s51, s51, 2
	s_add_u32 s22, s22, 0x100
	s_addc_u32 s23, s23, 0
	s_add_u32 s49, s49, 0x100
	s_addc_u32 s50, s50, 0
	s_cmp_gt_u32 s51, 13
	s_cbranch_scc0 .LBB0_225
	ds_read_b32 v224, v150
	ds_read_b32 v225, v150 offset:64
	ds_read_b32 v226, v150 offset:128
	ds_read_b32 v227, v150 offset:192
	ds_read_b32 v228, v150 offset:512
	ds_read_b32 v229, v150 offset:576
	ds_read_b32 v230, v150 offset:640
	ds_read_b32 v231, v150 offset:704
	s_and_b64 vcc, exec, s[10:11]
	s_cbranch_vccz .LBB0_228
	s_barrier
.LBB0_228:
	s_cmp_lg_u32 s20, s29
	s_cbranch_scc1 .Lsw_slow
	v_lshl_add_u32 v146, s20, 8, v148
	v_lshl_or_b32 v147, s4, 7, v151
	v_mul_u32_u24_e32 v146, 0x1600, v146
	v_lshl_add_u32 v146, v147, 1, v146
	s_waitcnt lgkmcnt(7)
	v_mul_f32_e32 v140, 0xbfb8aa3b, v224
	v_mul_f32_e32 v138, v224, v224
	v_pk_mul_f32 v[154:155], v[126:127], v[140:141] op_sel_hi:[1,0]
	v_pk_mul_f32 v[156:157], v[128:129], v[140:141] op_sel_hi:[1,0]
	v_pk_mul_f32 v[158:159], v[122:123], v[140:141] op_sel_hi:[1,0]
	v_pk_mul_f32 v[160:161], v[124:125], v[140:141] op_sel_hi:[1,0]
	v_exp_f32_e32 v154, v154
	v_exp_f32_e32 v155, v155
	v_exp_f32_e32 v156, v156
	v_exp_f32_e32 v157, v157
	v_exp_f32_e32 v158, v158
	v_exp_f32_e32 v159, v159
	v_exp_f32_e32 v160, v160
	v_exp_f32_e32 v161, v161
	v_pk_mul_f32 v[118:119], v[126:127], v[118:119]
	v_pk_mul_f32 v[120:121], v[128:129], v[120:121]
	v_pk_mul_f32 v[114:115], v[122:123], v[114:115]
	v_pk_mul_f32 v[116:117], v[124:125], v[116:117]
	v_pk_add_f32 v[154:155], v[154:155], 1.0 op_sel_hi:[1,0]
	v_pk_add_f32 v[156:157], v[156:157], 1.0 op_sel_hi:[1,0]
	v_pk_add_f32 v[158:159], v[158:159], 1.0 op_sel_hi:[1,0]
	v_pk_add_f32 v[160:161], v[160:161], 1.0 op_sel_hi:[1,0]
	v_pk_mul_f32 v[118:119], v[118:119], v[138:139] op_sel_hi:[1,0]
	v_pk_mul_f32 v[120:121], v[120:121], v[138:139] op_sel_hi:[1,0]
	v_pk_mul_f32 v[114:115], v[114:115], v[138:139] op_sel_hi:[1,0]
	v_pk_mul_f32 v[116:117], v[116:117], v[138:139] op_sel_hi:[1,0]
	v_rcp_f32_e32 v154, v154
	v_rcp_f32_e32 v155, v155
	v_rcp_f32_e32 v156, v156
	v_rcp_f32_e32 v157, v157
	v_rcp_f32_e32 v158, v158
	v_rcp_f32_e32 v159, v159
	v_rcp_f32_e32 v160, v160
	v_rcp_f32_e32 v161, v161
	v_pk_mul_f32 v[118:119], v[118:119], v[154:155]
	v_pk_mul_f32 v[120:121], v[120:121], v[156:157]
	v_pk_mul_f32 v[114:115], v[114:115], v[158:159]
	v_pk_mul_f32 v[116:117], v[116:117], v[160:161]
	v_cvt_pk_bf16_f32 v126, v118, v119
	v_cvt_pk_bf16_f32 v127, v120, v121
	v_cvt_pk_bf16_f32 v128, v114, v115
	v_cvt_pk_bf16_f32 v129, v116, v117
	global_store_dwordx4 v146, v[126:129], s[36:37] nt
	s_waitcnt lgkmcnt(6)
; __device__ __forceinline__ u32x4 pack8(const f32x4 a, const f32x4 b) { u32x4 w; w.x = cvt_pk_bf16(a[0], a[1]); w.y = cvt_pk_bf16(a[2], a[3]); w.z = cvt_pk_bf16(b[0], b[1]); w.w = cvt_pk_bf16(b[2], b[3]); return w; }
;     __device__ __forceinline__ void operator()(const f32x4 (&acc)[2][2][4][2], const Unit& u, int wr, int wc, int fr, int fq) const {
;     ...
;             for (int m = 0; m < 4; ++m) {
;                 const int row = row0 + ai * 128 + m * 16; const float rs = (u.pm == pm0) ? RS[row & 255] : row_rstd(ss, row), rsl = -LOG2E_ * rs, rs2 = rs * rs;
;                 f32x4 t[2], q[2], e[2];
; #pragma unroll
;                 for (int n = 0; n < 2; ++n) { t[n] = acc[ai][0][m][n] * rsl; q[n] = acc[ai][0][m][n] * acc[ai][1][m][n]; }
; #pragma unroll
;                 for (int n = 0; n < 2; ++n)
; #pragma unroll
;                     for (int j = 0; j < 4; ++j) e[n][j] = __builtin_amdgcn_exp2f(t[n][j]);
; #pragma unroll
;                 for (int n = 0; n < 2; ++n) { e[n] = e[n] + 1.0f; q[n] = q[n] * rs2; }
; #pragma unroll
;                 for (int n = 0; n < 2; ++n)
; #pragma unroll
;                     for (int j = 0; j < 4; ++j) e[n][j] = __builtin_amdgcn_rcpf(e[n][j]);
;                 __builtin_nontemporal_store(pack8(q[0] * e[0], q[1] * e[1]), (u32x4*)(O + (size_t)row * DFF + col0));
	v_mul_f32_e32 v140, 0xbfb8aa3b, v225
	v_mul_f32_e32 v138, v225, v225
	v_add_u32_e32 v147, 0x16000, v146
	v_pk_mul_f32 v[154:155], v[110:111], v[140:141] op_sel_hi:[1,0]
	v_pk_mul_f32 v[156:157], v[112:113], v[140:141] op_sel_hi:[1,0]
	v_pk_mul_f32 v[158:159], v[106:107], v[140:141] op_sel_hi:[1,0]
	v_pk_mul_f32 v[160:161], v[108:109], v[140:141] op_sel_hi:[1,0]
	v_exp_f32_e32 v154, v154
	v_exp_f32_e32 v155, v155
	v_exp_f32_e32 v156, v156
	v_exp_f32_e32 v157, v157
	v_exp_f32_e32 v158, v158
	v_exp_f32_e32 v159, v159
	v_exp_f32_e32 v160, v160
	v_exp_f32_e32 v161, v161
	v_pk_mul_f32 v[102:103], v[110:111], v[102:103]
	v_pk_mul_f32 v[104:105], v[112:113], v[104:105]
	v_pk_mul_f32 v[98:99], v[106:107], v[98:99]
	v_pk_mul_f32 v[100:101], v[108:109], v[100:101]
	v_pk_add_f32 v[154:155], v[154:155], 1.0 op_sel_hi:[1,0]
	v_pk_add_f32 v[156:157], v[156:157], 1.0 op_sel_hi:[1,0]
	v_pk_add_f32 v[158:159], v[158:159], 1.0 op_sel_hi:[1,0]
	v_pk_add_f32 v[160:161], v[160:161], 1.0 op_sel_hi:[1,0]
	v_pk_mul_f32 v[102:103], v[102:103], v[138:139] op_sel_hi:[1,0]
	v_pk_mul_f32 v[104:105], v[104:105], v[138:139] op_sel_hi:[1,0]
	v_pk_mul_f32 v[98:99], v[98:99], v[138:139] op_sel_hi:[1,0]
	v_pk_mul_f32 v[100:101], v[100:101], v[138:139] op_sel_hi:[1,0]
	v_rcp_f32_e32 v154, v154
	v_rcp_f32_e32 v155, v155
	v_rcp_f32_e32 v156, v156
	v_rcp_f32_e32 v157, v157
	v_rcp_f32_e32 v158, v158
	v_rcp_f32_e32 v159, v159
	v_rcp_f32_e32 v160, v160
	v_rcp_f32_e32 v161, v161
	v_pk_mul_f32 v[102:103], v[102:103], v[154:155]
	v_pk_mul_f32 v[104:105], v[104:105], v[156:157]
	v_pk_mul_f32 v[98:99], v[98:99], v[158:159]
	v_pk_mul_f32 v[100:101], v[100:101], v[160:161]
	v_cvt_pk_bf16_f32 v110, v102, v103
	v_cvt_pk_bf16_f32 v111, v104, v105
	v_cvt_pk_bf16_f32 v112, v98, v99
	v_cvt_pk_bf16_f32 v113, v100, v101
	global_store_dwordx4 v147, v[110:113], s[36:37] nt
	s_waitcnt lgkmcnt(5)
	v_mul_f32_e32 v140, 0xbfb8aa3b, v226
	v_mul_f32_e32 v138, v226, v226
	v_add_u32_e32 v147, 0x2c000, v146
	v_pk_mul_f32 v[154:155], v[94:95], v[140:141] op_sel_hi:[1,0]
	v_pk_mul_f32 v[156:157], v[96:97], v[140:141] op_sel_hi:[1,0]
	v_pk_mul_f32 v[158:159], v[90:91], v[140:141] op_sel_hi:[1,0]
	v_pk_mul_f32 v[160:161], v[92:93], v[140:141] op_sel_hi:[1,0]
	v_exp_f32_e32 v154, v154
	v_exp_f32_e32 v155, v155
	v_exp_f32_e32 v156, v156
	v_exp_f32_e32 v157, v157
	v_exp_f32_e32 v158, v158
	v_exp_f32_e32 v159, v159
	v_exp_f32_e32 v160, v160
	v_exp_f32_e32 v161, v161
	v_pk_mul_f32 v[86:87], v[94:95], v[86:87]
	v_pk_mul_f32 v[88:89], v[96:97], v[88:89]
	v_pk_mul_f32 v[82:83], v[90:91], v[82:83]
	v_pk_mul_f32 v[84:85], v[92:93], v[84:85]
	v_pk_add_f32 v[154:155], v[154:155], 1.0 op_sel_hi:[1,0]
	v_pk_add_f32 v[156:157], v[156:157], 1.0 op_sel_hi:[1,0]
	v_pk_add_f32 v[158:159], v[158:159], 1.0 op_sel_hi:[1,0]
	v_pk_add_f32 v[160:161], v[160:161], 1.0 op_sel_hi:[1,0]
	v_pk_mul_f32 v[86:87], v[86:87], v[138:139] op_sel_hi:[1,0]
	v_pk_mul_f32 v[88:89], v[88:89], v[138:139] op_sel_hi:[1,0]
	v_pk_mul_f32 v[82:83], v[82:83], v[138:139] op_sel_hi:[1,0]
	v_pk_mul_f32 v[84:85], v[84:85], v[138:139] op_sel_hi:[1,0]
	v_rcp_f32_e32 v154, v154
	v_rcp_f32_e32 v155, v155
	v_rcp_f32_e32 v156, v156
	v_rcp_f32_e32 v157, v157
	v_rcp_f32_e32 v158, v158
	v_rcp_f32_e32 v159, v159
	v_rcp_f32_e32 v160, v160
	v_rcp_f32_e32 v161, v161
	v_pk_mul_f32 v[86:87], v[86:87], v[154:155]
	v_pk_mul_f32 v[88:89], v[88:89], v[156:157]
	v_pk_mul_f32 v[82:83], v[82:83], v[158:159]
	v_pk_mul_f32 v[84:85], v[84:85], v[160:161]
	v_cvt_pk_bf16_f32 v94, v86, v87
	v_cvt_pk_bf16_f32 v95, v88, v89
	v_cvt_pk_bf16_f32 v96, v82, v83
	v_cvt_pk_bf16_f32 v97, v84, v85
	global_store_dwordx4 v147, v[94:97], s[36:37] nt
	s_waitcnt lgkmcnt(4)
	v_mul_f32_e32 v140, 0xbfb8aa3b, v227
	v_mul_f32_e32 v138, v227, v227
	v_add_u32_e32 v147, 0x42000, v146
	v_pk_mul_f32 v[154:155], v[78:79], v[140:141] op_sel_hi:[1,0]
	v_pk_mul_f32 v[156:157], v[80:81], v[140:141] op_sel_hi:[1,0]
	v_pk_mul_f32 v[158:159], v[74:75], v[140:141] op_sel_hi:[1,0]
	v_pk_mul_f32 v[160:161], v[76:77], v[140:141] op_sel_hi:[1,0]
	v_exp_f32_e32 v154, v154
	v_exp_f32_e32 v155, v155
	v_exp_f32_e32 v156, v156
	v_exp_f32_e32 v157, v157
	v_exp_f32_e32 v158, v158
	v_exp_f32_e32 v159, v159
	v_exp_f32_e32 v160, v160
	v_exp_f32_e32 v161, v161
	v_pk_mul_f32 v[70:71], v[78:79], v[70:71]
	v_pk_mul_f32 v[72:73], v[80:81], v[72:73]
	v_pk_mul_f32 v[66:67], v[74:75], v[66:67]
	v_pk_mul_f32 v[68:69], v[76:77], v[68:69]
	v_pk_add_f32 v[154:155], v[154:155], 1.0 op_sel_hi:[1,0]
	v_pk_add_f32 v[156:157], v[156:157], 1.0 op_sel_hi:[1,0]
	v_pk_add_f32 v[158:159], v[158:159], 1.0 op_sel_hi:[1,0]
	v_pk_add_f32 v[160:161], v[160:161], 1.0 op_sel_hi:[1,0]
	v_pk_mul_f32 v[70:71], v[70:71], v[138:139] op_sel_hi:[1,0]
	v_pk_mul_f32 v[72:73], v[72:73], v[138:139] op_sel_hi:[1,0]
	v_pk_mul_f32 v[66:67], v[66:67], v[138:139] op_sel_hi:[1,0]
	v_pk_mul_f32 v[68:69], v[68:69], v[138:139] op_sel_hi:[1,0]
	v_rcp_f32_e32 v154, v154
	v_rcp_f32_e32 v155, v155
	v_rcp_f32_e32 v156, v156
	v_rcp_f32_e32 v157, v157
	v_rcp_f32_e32 v158, v158
	v_rcp_f32_e32 v159, v159
	v_rcp_f32_e32 v160, v160
	v_rcp_f32_e32 v161, v161
	v_pk_mul_f32 v[70:71], v[70:71], v[154:155]
	v_pk_mul_f32 v[72:73], v[72:73], v[156:157]
	v_pk_mul_f32 v[66:67], v[66:67], v[158:159]
	v_pk_mul_f32 v[68:69], v[68:69], v[160:161]
	v_cvt_pk_bf16_f32 v78, v70, v71
	v_cvt_pk_bf16_f32 v79, v72, v73
	v_cvt_pk_bf16_f32 v80, v66, v67
	v_cvt_pk_bf16_f32 v81, v68, v69
	global_store_dwordx4 v147, v[78:81], s[36:37] nt
	s_waitcnt lgkmcnt(3)
; __device__ __forceinline__ u32x4 pack8(const f32x4 a, const f32x4 b) { u32x4 w; w.x = cvt_pk_bf16(a[0], a[1]); w.y = cvt_pk_bf16(a[2], a[3]); w.z = cvt_pk_bf16(b[0], b[1]); w.w = cvt_pk_bf16(b[2], b[3]); return w; }
;     __device__ __forceinline__ void operator()(const f32x4 (&acc)[2][2][4][2], const Unit& u, int wr, int wc, int fr, int fq) const {
;     ...
;             for (int m = 0; m < 4; ++m) {
;                 const int row = row0 + ai * 128 + m * 16; const float rs = (u.pm == pm0) ? RS[row & 255] : row_rstd(ss, row), rsl = -LOG2E_ * rs, rs2 = rs * rs;
;                 f32x4 t[2], q[2], e[2];
; #pragma unroll
;                 for (int n = 0; n < 2; ++n) { t[n] = acc[ai][0][m][n] * rsl; q[n] = acc[ai][0][m][n] * acc[ai][1][m][n]; }
; #pragma unroll
;                 for (int n = 0; n < 2; ++n)
; #pragma unroll
;                     for (int j = 0; j < 4; ++j) e[n][j] = __builtin_amdgcn_exp2f(t[n][j]);
; #pragma unroll
;                 for (int n = 0; n < 2; ++n) { e[n] = e[n] + 1.0f; q[n] = q[n] * rs2; }
; #pragma unroll
;                 for (int n = 0; n < 2; ++n)
; #pragma unroll
;                     for (int j = 0; j < 4; ++j) e[n][j] = __builtin_amdgcn_rcpf(e[n][j]);
;                 __builtin_nontemporal_store(pack8(q[0] * e[0], q[1] * e[1]), (u32x4*)(O + (size_t)row * DFF + col0));
	v_mul_f32_e32 v140, 0xbfb8aa3b, v228
	v_mul_f32_e32 v138, v228, v228
	v_add_u32_e32 v147, 0xb0000, v146
	v_pk_mul_f32 v[154:155], v[62:63], v[140:141] op_sel_hi:[1,0]
	v_pk_mul_f32 v[156:157], v[64:65], v[140:141] op_sel_hi:[1,0]
	v_pk_mul_f32 v[158:159], v[58:59], v[140:141] op_sel_hi:[1,0]
	v_pk_mul_f32 v[160:161], v[60:61], v[140:141] op_sel_hi:[1,0]
	v_exp_f32_e32 v154, v154
	v_exp_f32_e32 v155, v155
	v_exp_f32_e32 v156, v156
	v_exp_f32_e32 v157, v157
	v_exp_f32_e32 v158, v158
	v_exp_f32_e32 v159, v159
	v_exp_f32_e32 v160, v160
	v_exp_f32_e32 v161, v161
	v_pk_mul_f32 v[54:55], v[62:63], v[54:55]
	v_pk_mul_f32 v[56:57], v[64:65], v[56:57]
	v_pk_mul_f32 v[50:51], v[58:59], v[50:51]
	v_pk_mul_f32 v[52:53], v[60:61], v[52:53]
	v_pk_add_f32 v[154:155], v[154:155], 1.0 op_sel_hi:[1,0]
	v_pk_add_f32 v[156:157], v[156:157], 1.0 op_sel_hi:[1,0]
	v_pk_add_f32 v[158:159], v[158:159], 1.0 op_sel_hi:[1,0]
	v_pk_add_f32 v[160:161], v[160:161], 1.0 op_sel_hi:[1,0]
	v_pk_mul_f32 v[54:55], v[54:55], v[138:139] op_sel_hi:[1,0]
	v_pk_mul_f32 v[56:57], v[56:57], v[138:139] op_sel_hi:[1,0]
	v_pk_mul_f32 v[50:51], v[50:51], v[138:139] op_sel_hi:[1,0]
	v_pk_mul_f32 v[52:53], v[52:53], v[138:139] op_sel_hi:[1,0]
	v_rcp_f32_e32 v154, v154
	v_rcp_f32_e32 v155, v155
	v_rcp_f32_e32 v156, v156
	v_rcp_f32_e32 v157, v157
	v_rcp_f32_e32 v158, v158
	v_rcp_f32_e32 v159, v159
	v_rcp_f32_e32 v160, v160
	v_rcp_f32_e32 v161, v161
	v_pk_mul_f32 v[54:55], v[54:55], v[154:155]
	v_pk_mul_f32 v[56:57], v[56:57], v[156:157]
	v_pk_mul_f32 v[50:51], v[50:51], v[158:159]
	v_pk_mul_f32 v[52:53], v[52:53], v[160:161]
	v_cvt_pk_bf16_f32 v62, v54, v55
	v_cvt_pk_bf16_f32 v63, v56, v57
	v_cvt_pk_bf16_f32 v64, v50, v51
	v_cvt_pk_bf16_f32 v65, v52, v53
	global_store_dwordx4 v147, v[62:65], s[36:37] nt
	s_waitcnt lgkmcnt(2)
	v_mul_f32_e32 v140, 0xbfb8aa3b, v229
	v_mul_f32_e32 v138, v229, v229
	v_add_u32_e32 v147, 0xc6000, v146
	v_pk_mul_f32 v[154:155], v[46:47], v[140:141] op_sel_hi:[1,0]
	v_pk_mul_f32 v[156:157], v[48:49], v[140:141] op_sel_hi:[1,0]
	v_pk_mul_f32 v[158:159], v[42:43], v[140:141] op_sel_hi:[1,0]
	v_pk_mul_f32 v[160:161], v[44:45], v[140:141] op_sel_hi:[1,0]
	v_exp_f32_e32 v154, v154
	v_exp_f32_e32 v155, v155
	v_exp_f32_e32 v156, v156
	v_exp_f32_e32 v157, v157
	v_exp_f32_e32 v158, v158
	v_exp_f32_e32 v159, v159
	v_exp_f32_e32 v160, v160
	v_exp_f32_e32 v161, v161
	v_pk_mul_f32 v[38:39], v[46:47], v[38:39]
	v_pk_mul_f32 v[40:41], v[48:49], v[40:41]
	v_pk_mul_f32 v[34:35], v[42:43], v[34:35]
	v_pk_mul_f32 v[36:37], v[44:45], v[36:37]
	v_pk_add_f32 v[154:155], v[154:155], 1.0 op_sel_hi:[1,0]
	v_pk_add_f32 v[156:157], v[156:157], 1.0 op_sel_hi:[1,0]
	v_pk_add_f32 v[158:159], v[158:159], 1.0 op_sel_hi:[1,0]
	v_pk_add_f32 v[160:161], v[160:161], 1.0 op_sel_hi:[1,0]
	v_pk_mul_f32 v[38:39], v[38:39], v[138:139] op_sel_hi:[1,0]
	v_pk_mul_f32 v[40:41], v[40:41], v[138:139] op_sel_hi:[1,0]
	v_pk_mul_f32 v[34:35], v[34:35], v[138:139] op_sel_hi:[1,0]
	v_pk_mul_f32 v[36:37], v[36:37], v[138:139] op_sel_hi:[1,0]
	v_rcp_f32_e32 v154, v154
	v_rcp_f32_e32 v155, v155
	v_rcp_f32_e32 v156, v156
	v_rcp_f32_e32 v157, v157
	v_rcp_f32_e32 v158, v158
	v_rcp_f32_e32 v159, v159
	v_rcp_f32_e32 v160, v160
	v_rcp_f32_e32 v161, v161
	v_pk_mul_f32 v[38:39], v[38:39], v[154:155]
	v_pk_mul_f32 v[40:41], v[40:41], v[156:157]
	v_pk_mul_f32 v[34:35], v[34:35], v[158:159]
	v_pk_mul_f32 v[36:37], v[36:37], v[160:161]
	v_cvt_pk_bf16_f32 v46, v38, v39
	v_cvt_pk_bf16_f32 v47, v40, v41
	v_cvt_pk_bf16_f32 v48, v34, v35
	v_cvt_pk_bf16_f32 v49, v36, v37
	global_store_dwordx4 v147, v[46:49], s[36:37] nt
	s_waitcnt lgkmcnt(1)
; __device__ __forceinline__ u32x4 pack8(const f32x4 a, const f32x4 b) { u32x4 w; w.x = cvt_pk_bf16(a[0], a[1]); w.y = cvt_pk_bf16(a[2], a[3]); w.z = cvt_pk_bf16(b[0], b[1]); w.w = cvt_pk_bf16(b[2], b[3]); return w; }
;     __device__ __forceinline__ void operator()(const f32x4 (&acc)[2][2][4][2], const Unit& u, int wr, int wc, int fr, int fq) const {
;     ...
;             for (int m = 0; m < 4; ++m) {
;                 const int row = row0 + ai * 128 + m * 16; const float rs = (u.pm == pm0) ? RS[row & 255] : row_rstd(ss, row), rsl = -LOG2E_ * rs, rs2 = rs * rs;
;                 f32x4 t[2], q[2], e[2];
; #pragma unroll
;                 for (int n = 0; n < 2; ++n) { t[n] = acc[ai][0][m][n] * rsl; q[n] = acc[ai][0][m][n] * acc[ai][1][m][n]; }
; #pragma unroll
;                 for (int n = 0; n < 2; ++n)
; #pragma unroll
;                     for (int j = 0; j < 4; ++j) e[n][j] = __builtin_amdgcn_exp2f(t[n][j]);
; #pragma unroll
;                 for (int n = 0; n < 2; ++n) { e[n] = e[n] + 1.0f; q[n] = q[n] * rs2; }
; #pragma unroll
;                 for (int n = 0; n < 2; ++n)
; #pragma unroll
;                     for (int j = 0; j < 4; ++j) e[n][j] = __builtin_amdgcn_rcpf(e[n][j]);
;                 __builtin_nontemporal_store(pack8(q[0] * e[0], q[1] * e[1]), (u32x4*)(O + (size_t)row * DFF + col0));
	v_mul_f32_e32 v140, 0xbfb8aa3b, v230
	v_mul_f32_e32 v138, v230, v230
	v_add_u32_e32 v147, 0xdc000, v146
	v_pk_mul_f32 v[154:155], v[30:31], v[140:141] op_sel_hi:[1,0]
	v_pk_mul_f32 v[156:157], v[32:33], v[140:141] op_sel_hi:[1,0]
	v_pk_mul_f32 v[158:159], v[26:27], v[140:141] op_sel_hi:[1,0]
	v_pk_mul_f32 v[160:161], v[28:29], v[140:141] op_sel_hi:[1,0]
	v_exp_f32_e32 v154, v154
	v_exp_f32_e32 v155, v155
	v_exp_f32_e32 v156, v156
	v_exp_f32_e32 v157, v157
	v_exp_f32_e32 v158, v158
	v_exp_f32_e32 v159, v159
	v_exp_f32_e32 v160, v160
	v_exp_f32_e32 v161, v161
	v_pk_mul_f32 v[22:23], v[30:31], v[22:23]
	v_pk_mul_f32 v[24:25], v[32:33], v[24:25]
	v_pk_mul_f32 v[18:19], v[26:27], v[18:19]
	v_pk_mul_f32 v[20:21], v[28:29], v[20:21]
	v_pk_add_f32 v[154:155], v[154:155], 1.0 op_sel_hi:[1,0]
	v_pk_add_f32 v[156:157], v[156:157], 1.0 op_sel_hi:[1,0]
	v_pk_add_f32 v[158:159], v[158:159], 1.0 op_sel_hi:[1,0]
	v_pk_add_f32 v[160:161], v[160:161], 1.0 op_sel_hi:[1,0]
	v_pk_mul_f32 v[22:23], v[22:23], v[138:139] op_sel_hi:[1,0]
	v_pk_mul_f32 v[24:25], v[24:25], v[138:139] op_sel_hi:[1,0]
	v_pk_mul_f32 v[18:19], v[18:19], v[138:139] op_sel_hi:[1,0]
	v_pk_mul_f32 v[20:21], v[20:21], v[138:139] op_sel_hi:[1,0]
	v_rcp_f32_e32 v154, v154
	v_rcp_f32_e32 v155, v155
	v_rcp_f32_e32 v156, v156
	v_rcp_f32_e32 v157, v157
	v_rcp_f32_e32 v158, v158
	v_rcp_f32_e32 v159, v159
	v_rcp_f32_e32 v160, v160
	v_rcp_f32_e32 v161, v161
	v_pk_mul_f32 v[22:23], v[22:23], v[154:155]
	v_pk_mul_f32 v[24:25], v[24:25], v[156:157]
	v_pk_mul_f32 v[18:19], v[18:19], v[158:159]
	v_pk_mul_f32 v[20:21], v[20:21], v[160:161]
	v_cvt_pk_bf16_f32 v30, v22, v23
	v_cvt_pk_bf16_f32 v31, v24, v25
	v_cvt_pk_bf16_f32 v32, v18, v19
	v_cvt_pk_bf16_f32 v33, v20, v21
	global_store_dwordx4 v147, v[30:33], s[36:37] nt
	s_waitcnt lgkmcnt(0)
	v_mul_f32_e32 v140, 0xbfb8aa3b, v231
	v_mul_f32_e32 v138, v231, v231
	v_add_u32_e32 v147, 0xf2000, v146
	v_pk_mul_f32 v[154:155], v[14:15], v[140:141] op_sel_hi:[1,0]
	v_pk_mul_f32 v[156:157], v[16:17], v[140:141] op_sel_hi:[1,0]
	v_pk_mul_f32 v[158:159], v[10:11], v[140:141] op_sel_hi:[1,0]
	v_pk_mul_f32 v[160:161], v[12:13], v[140:141] op_sel_hi:[1,0]
	v_exp_f32_e32 v154, v154
	v_exp_f32_e32 v155, v155
	v_exp_f32_e32 v156, v156
	v_exp_f32_e32 v157, v157
	v_exp_f32_e32 v158, v158
	v_exp_f32_e32 v159, v159
	v_exp_f32_e32 v160, v160
	v_exp_f32_e32 v161, v161
	v_pk_mul_f32 v[6:7], v[14:15], v[6:7]
	v_pk_mul_f32 v[8:9], v[16:17], v[8:9]
	v_pk_mul_f32 v[2:3], v[10:11], v[2:3]
	v_pk_mul_f32 v[4:5], v[12:13], v[4:5]
	v_pk_add_f32 v[154:155], v[154:155], 1.0 op_sel_hi:[1,0]
	v_pk_add_f32 v[156:157], v[156:157], 1.0 op_sel_hi:[1,0]
	v_pk_add_f32 v[158:159], v[158:159], 1.0 op_sel_hi:[1,0]
	v_pk_add_f32 v[160:161], v[160:161], 1.0 op_sel_hi:[1,0]
	v_pk_mul_f32 v[6:7], v[6:7], v[138:139] op_sel_hi:[1,0]
	v_pk_mul_f32 v[8:9], v[8:9], v[138:139] op_sel_hi:[1,0]
	v_pk_mul_f32 v[2:3], v[2:3], v[138:139] op_sel_hi:[1,0]
	v_pk_mul_f32 v[4:5], v[4:5], v[138:139] op_sel_hi:[1,0]
	v_rcp_f32_e32 v154, v154
	v_rcp_f32_e32 v155, v155
	v_rcp_f32_e32 v156, v156
	v_rcp_f32_e32 v157, v157
	v_rcp_f32_e32 v158, v158
	v_rcp_f32_e32 v159, v159
	v_rcp_f32_e32 v160, v160
	v_rcp_f32_e32 v161, v161
	v_pk_mul_f32 v[6:7], v[6:7], v[154:155]
	v_pk_mul_f32 v[8:9], v[8:9], v[156:157]
	v_pk_mul_f32 v[2:3], v[2:3], v[158:159]
	v_pk_mul_f32 v[4:5], v[4:5], v[160:161]
	v_cvt_pk_bf16_f32 v14, v6, v7
	v_cvt_pk_bf16_f32 v15, v8, v9
	v_cvt_pk_bf16_f32 v16, v2, v3
	v_cvt_pk_bf16_f32 v17, v4, v5
	global_store_dwordx4 v147, v[14:17], s[36:37] nt
	s_andn2_b64 vcc, exec, s[2:3]
	s_mov_b64 s[2:3], -1
	s_cbranch_vccnz .LBB0_221
	s_branch .Lsw_join

; #define PG8_BAR __builtin_amdgcn_s_barrier()
; template <class Epi, class Sched, bool ALIGN_EPI = false, bool SP2 = false>
; __device__ __forceinline__ void gemm_phase(PG8_LAS unsigned char* lds, const Gemm g, const Sched& S, const Epi& E) {
;     ...
;         cur = nxt; cA = nA; cB = nB; ++ui;
;         if constexpr (ALIGN_EPI) { if (wr == 1) PG8_BAR; }
;     }
.Lsw_join:
	s_andn2_b64 vcc, exec, s[8:9]
	s_cbranch_vccnz .LBB0_220
	s_barrier
	s_branch .LBB0_220
